# grid barrier: the early L1 invalidate is issued (and waited for) by wave 1, so the leader's write-back / TOP arrival no longer waits behind it
# baseline (speedup 1.0000x reference)
.LBB0_276:
	s_cmp_lt_i32 s59, 2
	s_barrier
	s_cbranch_scc1 .LBB0_330
	s_waitcnt vmcnt(0)
	s_barrier
	s_cmp_eq_u32 s33, 64
	s_cbranch_scc0 .Lxb0_noinv
	buffer_inv sc1
	s_waitcnt vmcnt(0)
.Lxb0_noinv:
	s_and_saveexec_b64 s[2:3], s[0:1]
	s_cbranch_execz .LBB0_329
	s_waitcnt vmcnt(0) lgkmcnt(0)
	v_mov_b32_e32 v241, 0

.Lxb0_go:
	v_add_u32_e32 v246, 0x1400, v245
	global_atomic_add v248, v246, v247, s[60:61] sc0
	v_add_u32_e32 v249, 1, v244
	ds_write_b32 v241, v249 offset:8
	v_mul_lo_u32 v250, v249, v242
	v_mul_lo_u32 v251, v249, v243
	v_add_u32_e32 v253, 0x2400, v245
	v_mov_b32_e32 v252, 0
	s_waitcnt vmcnt(0)
	v_add_u32_e32 v248, 1, v248
	v_cmp_eq_u32_e32 vcc, v248, v250
	s_cbranch_vccz .Lxb0_wait
	buffer_wbl2 sc1
	s_waitcnt vmcnt(0)
	v_mov_b32_e32 v246, 0x3400
	global_atomic_add v248, v246, v247, s[60:61] sc0
	s_waitcnt vmcnt(0)
	v_add_u32_e32 v248, 1, v248

.LBB0_338:
	s_cmp_lt_i32 s59, 3
	s_barrier
	s_cbranch_scc1 .LBB0_392
	s_waitcnt vmcnt(0)
	s_barrier
	s_cmp_eq_u32 s33, 64
	s_cbranch_scc0 .Lxb1_noinv
	buffer_inv sc1
	s_waitcnt vmcnt(0)

.LBB0_587:
	s_cmp_lt_i32 s59, 4
	s_waitcnt vmcnt(0)
	s_barrier
	s_cbranch_scc1 .LBB0_641
	s_waitcnt vmcnt(0)
	s_barrier
	s_cmp_eq_u32 s33, 64
	s_cbranch_scc0 .Lxb2_noinv
	buffer_inv sc1
	s_waitcnt vmcnt(0)

.Lxb2_go:
	v_add_u32_e32 v246, 0x1400, v245
	global_atomic_add v248, v246, v247, s[60:61] sc0
	v_add_u32_e32 v249, 1, v244
	ds_write_b32 v241, v249 offset:8
	v_mul_lo_u32 v250, v249, v242
	v_mul_lo_u32 v251, v249, v243
	v_add_u32_e32 v253, 0x2400, v245
	v_mov_b32_e32 v252, 0
	s_waitcnt vmcnt(0)
	v_add_u32_e32 v248, 1, v248
	v_cmp_eq_u32_e32 vcc, v248, v250
	s_cbranch_vccz .Lxb2_wait
	s_waitcnt vmcnt(0)
	v_mov_b32_e32 v246, 0x3400
	global_atomic_add v248, v246, v247, s[60:61] sc0
	s_waitcnt vmcnt(0)
	v_add_u32_e32 v248, 1, v248

.LBB0_657:
	s_cmp_lt_i32 s59, 5
	s_barrier
	s_cbranch_scc1 .LBB0_711
	s_waitcnt vmcnt(0)
	s_barrier
	s_cmp_eq_u32 s33, 64
	s_cbranch_scc0 .Lxb3_noinv
	buffer_inv sc1
	s_waitcnt vmcnt(0)

.LBB0_833:
	s_cmp_lt_i32 s59, 6
	s_waitcnt vmcnt(0)
	s_barrier
	s_cbranch_scc1 .LBB0_887
	s_waitcnt vmcnt(0)
	s_barrier
	s_cmp_eq_u32 s33, 64
	s_cbranch_scc0 .Lxb4_noinv
	buffer_inv sc1
	s_waitcnt vmcnt(0)

.LBB0_986:
	s_cmp_lt_i32 s59, 7
	s_barrier
	s_cbranch_scc1 .LBB0_1040
	s_waitcnt vmcnt(0)
	s_barrier
	s_cmp_eq_u32 s33, 64
	s_cbranch_scc0 .Lxb5_noinv
	buffer_inv sc1
	s_waitcnt vmcnt(0)

.LBB0_1106:
	s_cmp_lt_i32 s59, 8
	s_barrier
	s_cbranch_scc1 .LBB0_1160
	s_waitcnt vmcnt(0)
	s_barrier
	s_cmp_eq_u32 s33, 64
	s_cbranch_scc0 .Lxb6_noinv
	buffer_inv sc1
	s_waitcnt vmcnt(0)

.LBB0_1285:
	s_cmp_lt_i32 s59, 10
	s_waitcnt vmcnt(0)
	s_barrier
	s_cbranch_scc1 .LBB0_1339
	s_waitcnt vmcnt(0)
	s_barrier
	s_cmp_eq_u32 s33, 64
	s_cbranch_scc0 .Lxb7_noinv
	buffer_inv sc1
	s_waitcnt vmcnt(0)

.LBB0_1347:
	s_cmp_lt_i32 s59, 11
	s_barrier
	s_cbranch_scc1 .LBB0_1401
	s_waitcnt vmcnt(0)
	s_barrier
	s_cmp_eq_u32 s33, 64
	s_cbranch_scc0 .Lxb8_noinv
	buffer_inv sc1
	s_waitcnt vmcnt(0)

.LBB0_1558:
	s_cmp_lt_i32 s59, 12
	s_waitcnt lgkmcnt(0)
	s_barrier
	s_cbranch_scc1 .LBB0_1612
	s_waitcnt vmcnt(0)
	s_barrier
	s_cmp_eq_u32 s33, 64
	s_cbranch_scc0 .Lxb9_noinv
	buffer_inv sc1
	s_waitcnt vmcnt(0)

.LBB0_2400:
	s_cmp_lt_i32 s59, 14
	s_waitcnt vmcnt(0)
	s_barrier
	s_cbranch_scc1 .LBB0_2454
	s_waitcnt vmcnt(0)
	s_barrier
	s_cmp_eq_u32 s33, 64
	s_cbranch_scc0 .Lxb10_noinv
	buffer_inv sc1
	s_waitcnt vmcnt(0)

.LBB0_2462:
	s_cmp_lt_i32 s59, 15
	s_barrier
	s_cbranch_scc1 .LBB0_2516
	s_waitcnt vmcnt(0)
	s_barrier
	s_cmp_eq_u32 s33, 64
	s_cbranch_scc0 .Lxb11_noinv
	buffer_inv sc1
	s_waitcnt vmcnt(0)

.LBB0_2579:
	s_cmp_lt_i32 s59, 16
	s_waitcnt vmcnt(0)
	s_barrier
	s_cbranch_scc1 .LBB0_2634
	s_waitcnt vmcnt(0)
	s_barrier
	s_cmp_eq_u32 s33, 64
	s_cbranch_scc0 .Lxb12_noinv
	buffer_inv sc1
	s_waitcnt vmcnt(0)

.LBB0_2702:
	s_cmp_lt_i32 s59, 17
	s_barrier
	s_cbranch_scc1 .LBB0_2756
	s_waitcnt vmcnt(0)
	s_barrier
	s_cmp_eq_u32 s33, 64
	s_cbranch_scc0 .Lxb13_noinv
	buffer_inv sc1
	s_waitcnt vmcnt(0)

.LBB0_2844:
	s_cmp_lt_i32 s59, 18
	s_barrier
	s_cbranch_scc1 .LBB0_2898
	s_waitcnt vmcnt(0)
	s_barrier
	s_cmp_eq_u32 s33, 64
	s_cbranch_scc0 .Lxb14_noinv
	buffer_inv sc1
	s_waitcnt vmcnt(0)

.LBB0_3024:
	s_cmp_lt_i32 s59, 20
	s_waitcnt vmcnt(0)
	s_barrier
	s_cbranch_scc1 .LBB0_3078
	s_waitcnt vmcnt(0)
	s_barrier
	s_cmp_eq_u32 s33, 64
	s_cbranch_scc0 .Lxb15_noinv
	buffer_inv sc1
	s_waitcnt vmcnt(0)

.LBB0_3082:
	s_cmp_lt_u32 s59, 21
	s_barrier
	s_cbranch_scc1 .LBB0_3136
	s_waitcnt vmcnt(0)
	s_barrier
	s_cmp_eq_u32 s33, 64
	s_cbranch_scc0 .Lxb16_noinv
	buffer_inv sc1
	s_waitcnt vmcnt(0)

.LBB0_3155:
	s_cmp_lt_i32 s59, 22
	s_waitcnt vmcnt(0)
	s_barrier
	s_cbranch_scc1 .LBB0_3209
	s_waitcnt vmcnt(0)
	s_barrier
	s_cmp_eq_u32 s33, 64
	s_cbranch_scc0 .Lxb17_noinv
	buffer_inv sc1
	s_waitcnt vmcnt(0)

.LBB0_3217:
	s_cmp_lt_i32 s59, 23
	s_barrier
	s_cbranch_scc1 .LBB0_3271
	s_waitcnt vmcnt(0)
	s_barrier
	s_cmp_eq_u32 s33, 64
	s_cbranch_scc0 .Lxb18_noinv
	buffer_inv sc1
	s_waitcnt vmcnt(0)

.LBB0_3341:
	s_cmp_lt_i32 s59, 24
	s_waitcnt lgkmcnt(0)
	s_barrier
	s_cbranch_scc1 .LBB0_3395
	s_waitcnt vmcnt(0)
	s_barrier
	s_cmp_eq_u32 s33, 64
	s_cbranch_scc0 .Lxb19_noinv
	buffer_inv sc1
	s_waitcnt vmcnt(0)

.LBB0_3517:
	s_cmp_lt_i32 s59, 26
	s_waitcnt vmcnt(0)
	s_barrier
	s_cbranch_scc1 .LBB0_3571
	s_waitcnt vmcnt(0)
	s_barrier
	s_cmp_eq_u32 s33, 64
	s_cbranch_scc0 .Lxb20_noinv
	buffer_inv sc1
	s_waitcnt vmcnt(0)
